# GU main loop back-edge rotation (7.11): loop-head address SALU/VALU moved in front of the loop-back barrier in the loop tail and the peeled iteration tail
# baseline (speedup 1.0000x reference)
.LBB0_791:
	v_mov_b64_e32 v[0:1], 0x580
	s_ashr_i32 s21, s20, 31
	v_cmp_lt_i64_e32 vcc, s[22:23], v[0:1]
	s_lshl_b64 s[22:23], s[20:21], 19
	s_add_u32 s22, s96, s22
	s_addc_u32 s23, s97, s23
	s_and_b64 s[24:25], vcc, exec
	s_cselect_b32 s9, s23, s59
	s_cselect_b32 s21, s22, s58
	s_ashr_i32 s19, s18, 31
	s_lshl_b64 s[24:25], s[18:19], 19
	s_add_u32 s24, s35, s24
	s_addc_u32 s25, s47, s25
	s_and_b64 s[66:67], vcc, exec
	s_cselect_b32 s19, s25, s63
	s_cselect_b32 s29, s24, s62
	s_add_u32 s58, s58, 0x40080
	s_addc_u32 s59, s59, 0
	s_add_u32 s43, s62, 0x100
	s_addc_u32 s51, s63, 0
	s_mov_b32 s75, -2
	s_add_u32 s62, s58, 0xfffc0080
	s_addc_u32 s63, s59, -1
	s_add_i32 s76, 0, 0x10000
	v_add_u32_e32 v138, s76, v142
	ds_read_b128 v[146:149], v138
	ds_read_b128 v[150:153], v138 offset:1024
	ds_read_b128 v[166:169], v138 offset:2048
	ds_read_b128 v[170:173], v138 offset:3072
	s_cmp_eq_u32 s75, 12
	s_cselect_b32 s67, s9, s63
	s_cselect_b32 s66, s21, s62
	s_cselect_b32 s63, s19, s51
	s_cselect_b32 s62, s29, s43
	s_add_i32 m0, s48, 0xc000
	ds_read_b128 v[174:177], v145
	ds_read_b128 v[178:181], v145 offset:1024
	ds_read_b128 v[182:185], v145 offset:2048
	ds_read_b128 v[186:189], v145 offset:3072
	ds_read_b128 v[214:217], v145 offset:4096
	ds_read_b128 v[218:221], v145 offset:5120
	ds_read_b128 v[222:225], v145 offset:6144
	ds_read_b128 v[226:229], v145 offset:7168
	global_load_lds_dwordx4 v134, s[58:59]
	s_add_i32 m0, s48, 0xe000
	s_nop 0
	global_load_lds_dwordx4 v136, s[58:59]
	s_waitcnt lgkmcnt(8)
	s_barrier
	s_waitcnt lgkmcnt(0)
	s_setprio 1
	s_waitcnt lgkmcnt(0)
	v_mfma_f32_16x16x32_bf16 v[124:127], v[146:149], v[174:177], 0
	v_mfma_f32_16x16x32_bf16 v[116:119], v[166:169], v[174:177], 0
	v_mfma_f32_16x16x32_bf16 v[108:111], v[146:149], v[182:185], 0
	v_mfma_f32_16x16x32_bf16 v[100:103], v[166:169], v[182:185], 0
	v_mfma_f32_16x16x32_bf16 v[92:95], v[146:149], v[214:217], 0
	v_mfma_f32_16x16x32_bf16 v[84:87], v[166:169], v[214:217], 0
	v_mfma_f32_16x16x32_bf16 v[76:79], v[146:149], v[222:225], 0
	v_mfma_f32_16x16x32_bf16 v[68:71], v[166:169], v[222:225], 0
	v_mfma_f32_16x16x32_bf16 v[124:127], v[150:153], v[178:181], v[124:127]
	v_mfma_f32_16x16x32_bf16 v[116:119], v[170:173], v[178:181], v[116:119]
	v_mfma_f32_16x16x32_bf16 v[108:111], v[150:153], v[186:189], v[108:111]
	v_mfma_f32_16x16x32_bf16 v[100:103], v[170:173], v[186:189], v[100:103]
	v_mfma_f32_16x16x32_bf16 v[92:95], v[150:153], v[218:221], v[92:95]
	v_mfma_f32_16x16x32_bf16 v[84:87], v[170:173], v[218:221], v[84:87]
	v_mfma_f32_16x16x32_bf16 v[76:79], v[150:153], v[226:229], v[76:79]
	v_mfma_f32_16x16x32_bf16 v[68:71], v[170:173], v[226:229], v[68:71]
	s_setprio 0
	s_barrier
	s_add_i32 s78, 0, 0x14000
	v_add_u32_e32 v138, s78, v142
	s_add_i32 s76, s76, s31
	ds_read_b128 v[230:233], v138
	ds_read_b128 v[234:237], v138 offset:1024
	ds_read_b128 v[238:241], v138 offset:2048
	ds_read_b128 v[242:245], v138 offset:3072
	v_lshl_add_u64 v[138:139], s[62:63], 0, v[158:159]
	s_mov_b32 m0, s76
	v_lshl_add_u64 v[154:155], s[62:63], 0, v[132:133]
	global_load_lds_dwordx4 v158, s[62:63]
	s_add_i32 m0, s76, 0x2000
	s_nop 0
	global_load_lds_dwordx4 v132, s[62:63]
	s_barrier
	s_waitcnt lgkmcnt(0)
	s_setprio 1
	s_waitcnt lgkmcnt(0)
	v_mfma_f32_16x16x32_bf16 v[120:123], v[230:233], v[174:177], 0
	v_mfma_f32_16x16x32_bf16 v[112:115], v[238:241], v[174:177], 0
	v_mfma_f32_16x16x32_bf16 v[104:107], v[230:233], v[182:185], 0
	v_mfma_f32_16x16x32_bf16 v[96:99], v[238:241], v[182:185], 0
	v_mfma_f32_16x16x32_bf16 v[88:91], v[230:233], v[214:217], 0
	v_mfma_f32_16x16x32_bf16 v[80:83], v[238:241], v[214:217], 0
	v_mfma_f32_16x16x32_bf16 v[72:75], v[230:233], v[222:225], 0
	v_mfma_f32_16x16x32_bf16 v[64:67], v[238:241], v[222:225], 0
	v_mfma_f32_16x16x32_bf16 v[120:123], v[234:237], v[178:181], v[120:123]
	v_mfma_f32_16x16x32_bf16 v[112:115], v[242:245], v[178:181], v[112:115]
	v_mfma_f32_16x16x32_bf16 v[104:107], v[234:237], v[186:189], v[104:107]
	v_mfma_f32_16x16x32_bf16 v[96:99], v[242:245], v[186:189], v[96:99]
	v_mfma_f32_16x16x32_bf16 v[88:91], v[234:237], v[218:221], v[88:91]
	v_mfma_f32_16x16x32_bf16 v[80:83], v[242:245], v[218:221], v[80:83]
	v_mfma_f32_16x16x32_bf16 v[72:75], v[234:237], v[226:229], v[72:75]
	v_mfma_f32_16x16x32_bf16 v[64:67], v[242:245], v[226:229], v[64:67]
	s_setprio 0
	s_mov_b32 m0, s48
	v_lshl_add_u64 v[190:191], s[66:67], 0, v[128:129]
	s_barrier
	ds_read_b128 v[174:177], v145 offset:16384
	ds_read_b128 v[178:181], v145 offset:17408
	ds_read_b128 v[182:185], v145 offset:18432
	ds_read_b128 v[186:189], v145 offset:19456
	ds_read_b128 v[214:217], v145 offset:20480
	ds_read_b128 v[218:221], v145 offset:21504
	ds_read_b128 v[222:225], v145 offset:22528
	ds_read_b128 v[226:229], v145 offset:23552
	global_load_lds_dwordx4 v128, s[66:67]
	v_lshl_add_u64 v[202:203], s[66:67], 0, v[130:131]
	s_mov_b32 m0, s50
	s_nop 0
	global_load_lds_dwordx4 v130, s[66:67]
	s_barrier
	s_waitcnt lgkmcnt(0)
	s_setprio 1
	s_waitcnt lgkmcnt(0)
	v_mfma_f32_16x16x32_bf16 v[60:63], v[146:149], v[174:177], 0
	v_mfma_f32_16x16x32_bf16 v[52:55], v[166:169], v[174:177], 0
	v_mfma_f32_16x16x32_bf16 v[44:47], v[146:149], v[182:185], 0
	v_mfma_f32_16x16x32_bf16 v[36:39], v[166:169], v[182:185], 0
	v_mfma_f32_16x16x32_bf16 v[28:31], v[146:149], v[214:217], 0
	v_mfma_f32_16x16x32_bf16 v[20:23], v[166:169], v[214:217], 0
	v_mfma_f32_16x16x32_bf16 v[12:15], v[146:149], v[222:225], 0
	v_mfma_f32_16x16x32_bf16 v[4:7], v[166:169], v[222:225], 0
	v_mfma_f32_16x16x32_bf16 v[60:63], v[150:153], v[178:181], v[60:63]
	v_mfma_f32_16x16x32_bf16 v[52:55], v[170:173], v[178:181], v[52:55]
	v_mfma_f32_16x16x32_bf16 v[44:47], v[150:153], v[186:189], v[44:47]
	v_mfma_f32_16x16x32_bf16 v[36:39], v[170:173], v[186:189], v[36:39]
	v_mfma_f32_16x16x32_bf16 v[28:31], v[150:153], v[218:221], v[28:31]
	v_mfma_f32_16x16x32_bf16 v[20:23], v[170:173], v[218:221], v[20:23]
	v_mfma_f32_16x16x32_bf16 v[12:15], v[150:153], v[226:229], v[12:15]
	v_mfma_f32_16x16x32_bf16 v[4:7], v[170:173], v[226:229], v[4:7]
	s_setprio 0
	s_barrier
	s_add_u32 s76, s62, 0x40000
	s_addc_u32 s77, s63, 0
	s_add_i32 s78, s78, s31
	s_mov_b32 m0, s78
	s_nop 0
	global_load_lds_dwordx4 v158, s[76:77]
	s_add_i32 m0, s78, 0x2000
	s_nop 0
	global_load_lds_dwordx4 v132, s[76:77]
	s_waitcnt vmcnt(6)
	s_barrier
	s_setprio 1
	v_mfma_f32_16x16x32_bf16 v[56:59], v[230:233], v[174:177], 0
	v_mfma_f32_16x16x32_bf16 v[48:51], v[238:241], v[174:177], 0
	v_mfma_f32_16x16x32_bf16 v[40:43], v[230:233], v[182:185], 0
	v_mfma_f32_16x16x32_bf16 v[32:35], v[238:241], v[182:185], 0
	v_mfma_f32_16x16x32_bf16 v[24:27], v[230:233], v[214:217], 0
	v_mfma_f32_16x16x32_bf16 v[16:19], v[238:241], v[214:217], 0
	v_mfma_f32_16x16x32_bf16 v[8:11], v[230:233], v[222:225], 0
	v_mfma_f32_16x16x32_bf16 v[0:3], v[238:241], v[222:225], 0
	v_mfma_f32_16x16x32_bf16 v[56:59], v[234:237], v[178:181], v[56:59]
	v_mfma_f32_16x16x32_bf16 v[48:51], v[242:245], v[178:181], v[48:51]
	v_mfma_f32_16x16x32_bf16 v[40:43], v[234:237], v[186:189], v[40:43]
	v_mfma_f32_16x16x32_bf16 v[32:35], v[242:245], v[186:189], v[32:35]
	v_mfma_f32_16x16x32_bf16 v[24:27], v[234:237], v[218:221], v[24:27]
	v_mfma_f32_16x16x32_bf16 v[16:19], v[242:245], v[218:221], v[16:19]
	v_mfma_f32_16x16x32_bf16 v[8:11], v[234:237], v[226:229], v[8:11]
	v_mfma_f32_16x16x32_bf16 v[0:3], v[242:245], v[226:229], v[0:3]
	s_setprio 0
	s_add_i32 s76, 0, 0x18000
	v_add_u32_e32 v140, s76, v142
	s_barrier
	ds_read_b128 v[146:149], v140
	ds_read_b128 v[150:153], v140 offset:1024
	ds_read_b128 v[166:169], v140 offset:2048
	ds_read_b128 v[170:173], v140 offset:3072
	s_add_u32 s66, s66, 0x40000
	s_addc_u32 s67, s67, 0
	s_mov_b32 m0, s65
	ds_read_b128 v[174:177], v145 offset:32768
	ds_read_b128 v[178:181], v145 offset:33792
	ds_read_b128 v[182:185], v145 offset:34816
	ds_read_b128 v[186:189], v145 offset:35840
	ds_read_b128 v[214:217], v145 offset:36864
	ds_read_b128 v[218:221], v145 offset:37888
	ds_read_b128 v[222:225], v145 offset:38912
	ds_read_b128 v[226:229], v145 offset:39936
	global_load_lds_dwordx4 v128, s[66:67]
	s_mov_b32 m0, s68
	s_nop 0
	global_load_lds_dwordx4 v130, s[66:67]
	s_waitcnt lgkmcnt(8)
	s_barrier
	s_waitcnt lgkmcnt(0)
	s_setprio 1
	s_waitcnt lgkmcnt(0)
	v_mfma_f32_16x16x32_bf16 v[124:127], v[146:149], v[174:177], v[124:127]
	v_mfma_f32_16x16x32_bf16 v[116:119], v[166:169], v[174:177], v[116:119]
	v_mfma_f32_16x16x32_bf16 v[108:111], v[146:149], v[182:185], v[108:111]
	v_mfma_f32_16x16x32_bf16 v[100:103], v[166:169], v[182:185], v[100:103]
	v_mfma_f32_16x16x32_bf16 v[92:95], v[146:149], v[214:217], v[92:95]
	v_mfma_f32_16x16x32_bf16 v[84:87], v[166:169], v[214:217], v[84:87]
	v_mfma_f32_16x16x32_bf16 v[76:79], v[146:149], v[222:225], v[76:79]
	v_mfma_f32_16x16x32_bf16 v[68:71], v[166:169], v[222:225], v[68:71]
	v_mfma_f32_16x16x32_bf16 v[124:127], v[150:153], v[178:181], v[124:127]
	v_mfma_f32_16x16x32_bf16 v[116:119], v[170:173], v[178:181], v[116:119]
	v_mfma_f32_16x16x32_bf16 v[108:111], v[150:153], v[186:189], v[108:111]
	v_mfma_f32_16x16x32_bf16 v[100:103], v[170:173], v[186:189], v[100:103]
	v_mfma_f32_16x16x32_bf16 v[92:95], v[150:153], v[218:221], v[92:95]
	v_mfma_f32_16x16x32_bf16 v[84:87], v[170:173], v[218:221], v[84:87]
	v_mfma_f32_16x16x32_bf16 v[76:79], v[150:153], v[226:229], v[76:79]
	v_mfma_f32_16x16x32_bf16 v[68:71], v[170:173], v[226:229], v[68:71]
	s_setprio 0
	s_barrier
	s_add_i32 s66, 0, 0x1c000
	s_add_i32 s67, s76, s31
	v_add_u32_e32 v140, s66, v142
	v_lshl_add_u64 v[138:139], v[138:139], 0, s[70:71]
	s_mov_b32 m0, s67
	ds_read_b128 v[230:233], v140
	ds_read_b128 v[234:237], v140 offset:1024
	ds_read_b128 v[238:241], v140 offset:2048
	ds_read_b128 v[242:245], v140 offset:3072
	global_load_lds_dwordx4 v[138:139], off
	v_lshl_add_u64 v[138:139], v[154:155], 0, s[70:71]
	s_add_i32 m0, s67, 0x2000
	s_nop 0
	global_load_lds_dwordx4 v[138:139], off
	s_barrier
	s_waitcnt lgkmcnt(0)
	s_setprio 1
	s_waitcnt lgkmcnt(0)
	v_mfma_f32_16x16x32_bf16 v[120:123], v[230:233], v[174:177], v[120:123]
	v_mfma_f32_16x16x32_bf16 v[112:115], v[238:241], v[174:177], v[112:115]
	v_mfma_f32_16x16x32_bf16 v[104:107], v[230:233], v[182:185], v[104:107]
	v_mfma_f32_16x16x32_bf16 v[96:99], v[238:241], v[182:185], v[96:99]
	v_mfma_f32_16x16x32_bf16 v[88:91], v[230:233], v[214:217], v[88:91]
	v_mfma_f32_16x16x32_bf16 v[80:83], v[238:241], v[214:217], v[80:83]
	v_mfma_f32_16x16x32_bf16 v[72:75], v[230:233], v[222:225], v[72:75]
	v_mfma_f32_16x16x32_bf16 v[64:67], v[238:241], v[222:225], v[64:67]
	v_mfma_f32_16x16x32_bf16 v[120:123], v[234:237], v[178:181], v[120:123]
	v_mfma_f32_16x16x32_bf16 v[112:115], v[242:245], v[178:181], v[112:115]
	v_mfma_f32_16x16x32_bf16 v[104:107], v[234:237], v[186:189], v[104:107]
	v_mfma_f32_16x16x32_bf16 v[96:99], v[242:245], v[186:189], v[96:99]
	v_mfma_f32_16x16x32_bf16 v[88:91], v[234:237], v[218:221], v[88:91]
	v_mfma_f32_16x16x32_bf16 v[80:83], v[242:245], v[218:221], v[80:83]
	v_mfma_f32_16x16x32_bf16 v[72:75], v[234:237], v[226:229], v[72:75]
	v_mfma_f32_16x16x32_bf16 v[64:67], v[242:245], v[226:229], v[64:67]
	s_setprio 0
	s_mov_b32 m0, s69
	v_lshl_add_u64 v[138:139], v[190:191], 0, s[70:71]
	s_barrier
	ds_read_b128 v[174:177], v145 offset:49152
	ds_read_b128 v[178:181], v145 offset:50176
	ds_read_b128 v[182:185], v145 offset:51200
	ds_read_b128 v[186:189], v145 offset:52224
	ds_read_b128 v[214:217], v145 offset:53248
	ds_read_b128 v[218:221], v145 offset:54272
	ds_read_b128 v[222:225], v145 offset:55296
	ds_read_b128 v[226:229], v145 offset:56320
	global_load_lds_dwordx4 v[138:139], off
	v_lshl_add_u64 v[138:139], v[202:203], 0, s[70:71]
	s_mov_b32 m0, s72
	s_nop 0
	global_load_lds_dwordx4 v[138:139], off
	s_barrier
	s_waitcnt lgkmcnt(0)
	s_setprio 1
	s_waitcnt lgkmcnt(0)
	v_mfma_f32_16x16x32_bf16 v[60:63], v[146:149], v[174:177], v[60:63]
	v_mfma_f32_16x16x32_bf16 v[52:55], v[166:169], v[174:177], v[52:55]
	v_mfma_f32_16x16x32_bf16 v[44:47], v[146:149], v[182:185], v[44:47]
	v_mfma_f32_16x16x32_bf16 v[36:39], v[166:169], v[182:185], v[36:39]
	v_mfma_f32_16x16x32_bf16 v[28:31], v[146:149], v[214:217], v[28:31]
	v_mfma_f32_16x16x32_bf16 v[20:23], v[166:169], v[214:217], v[20:23]
	v_mfma_f32_16x16x32_bf16 v[12:15], v[146:149], v[222:225], v[12:15]
	v_mfma_f32_16x16x32_bf16 v[4:7], v[166:169], v[222:225], v[4:7]
	v_mfma_f32_16x16x32_bf16 v[60:63], v[150:153], v[178:181], v[60:63]
	v_mfma_f32_16x16x32_bf16 v[52:55], v[170:173], v[178:181], v[52:55]
	v_mfma_f32_16x16x32_bf16 v[44:47], v[150:153], v[186:189], v[44:47]
	v_mfma_f32_16x16x32_bf16 v[36:39], v[170:173], v[186:189], v[36:39]
	v_mfma_f32_16x16x32_bf16 v[28:31], v[150:153], v[218:221], v[28:31]
	v_mfma_f32_16x16x32_bf16 v[20:23], v[170:173], v[218:221], v[20:23]
	v_mfma_f32_16x16x32_bf16 v[12:15], v[150:153], v[226:229], v[12:15]
	v_mfma_f32_16x16x32_bf16 v[4:7], v[170:173], v[226:229], v[4:7]
	s_setprio 0
	s_barrier
	s_add_u32 s62, s62, 0x40080
	s_addc_u32 s63, s63, 0
	s_add_i32 s66, s66, s31
	s_mov_b32 m0, s66
	s_nop 0
	global_load_lds_dwordx4 v158, s[62:63]
	s_add_i32 m0, s66, 0x2000
	s_nop 0
	global_load_lds_dwordx4 v132, s[62:63]
	s_waitcnt vmcnt(6)
	s_barrier
	s_setprio 1
	v_mfma_f32_16x16x32_bf16 v[56:59], v[230:233], v[174:177], v[56:59]
	v_mfma_f32_16x16x32_bf16 v[48:51], v[238:241], v[174:177], v[48:51]
	v_mfma_f32_16x16x32_bf16 v[40:43], v[230:233], v[182:185], v[40:43]
	v_mfma_f32_16x16x32_bf16 v[32:35], v[238:241], v[182:185], v[32:35]
	v_mfma_f32_16x16x32_bf16 v[24:27], v[230:233], v[214:217], v[24:27]
	v_mfma_f32_16x16x32_bf16 v[16:19], v[238:241], v[214:217], v[16:19]
	v_mfma_f32_16x16x32_bf16 v[8:11], v[230:233], v[222:225], v[8:11]
	v_mfma_f32_16x16x32_bf16 v[0:3], v[238:241], v[222:225], v[0:3]
	v_mfma_f32_16x16x32_bf16 v[56:59], v[234:237], v[178:181], v[56:59]
	v_mfma_f32_16x16x32_bf16 v[48:51], v[242:245], v[178:181], v[48:51]
	v_mfma_f32_16x16x32_bf16 v[40:43], v[234:237], v[186:189], v[40:43]
	v_mfma_f32_16x16x32_bf16 v[32:35], v[242:245], v[186:189], v[32:35]
	v_mfma_f32_16x16x32_bf16 v[24:27], v[234:237], v[218:221], v[24:27]
	v_mfma_f32_16x16x32_bf16 v[16:19], v[242:245], v[218:221], v[16:19]
	v_mfma_f32_16x16x32_bf16 v[8:11], v[234:237], v[226:229], v[8:11]
	v_mfma_f32_16x16x32_bf16 v[0:3], v[242:245], v[226:229], v[0:3]
	s_setprio 0
	s_add_i32 s75, s75, 2
	s_add_u32 s58, s58, 0x100
	s_addc_u32 s59, s59, 0
	s_add_u32 s43, s43, 0x100
	s_addc_u32 s51, s51, 0
	s_add_u32 s62, s58, 0xfffc0080
	s_addc_u32 s63, s59, -1
	s_add_i32 s76, 0, 0x10000
	v_add_u32_e32 v138, s76, v142
	s_cmp_gt_u32 s75, 13
	s_barrier
	s_cbranch_scc1 .Lzp_exit3
.LBB0_792:
	ds_read_b128 v[146:149], v138
	ds_read_b128 v[150:153], v138 offset:1024
	ds_read_b128 v[166:169], v138 offset:2048
	ds_read_b128 v[170:173], v138 offset:3072
	s_cmp_eq_u32 s75, 12
	s_cselect_b32 s67, s9, s63
	s_cselect_b32 s66, s21, s62
	s_cselect_b32 s63, s19, s51
	s_cselect_b32 s62, s29, s43
	s_add_i32 m0, s48, 0xc000
	ds_read_b128 v[174:177], v145
	ds_read_b128 v[178:181], v145 offset:1024
	ds_read_b128 v[182:185], v145 offset:2048
	ds_read_b128 v[186:189], v145 offset:3072
	ds_read_b128 v[214:217], v145 offset:4096
	ds_read_b128 v[218:221], v145 offset:5120
	ds_read_b128 v[222:225], v145 offset:6144
	ds_read_b128 v[226:229], v145 offset:7168
	global_load_lds_dwordx4 v134, s[58:59]
	s_add_i32 m0, s48, 0xe000
	s_nop 0
	global_load_lds_dwordx4 v136, s[58:59]
	s_waitcnt lgkmcnt(8)
	s_barrier
	s_waitcnt lgkmcnt(0)
	s_setprio 1
	s_waitcnt lgkmcnt(0)
	v_mfma_f32_16x16x32_bf16 v[124:127], v[146:149], v[174:177], v[124:127]
	v_mfma_f32_16x16x32_bf16 v[116:119], v[166:169], v[174:177], v[116:119]
	v_mfma_f32_16x16x32_bf16 v[108:111], v[146:149], v[182:185], v[108:111]
	v_mfma_f32_16x16x32_bf16 v[100:103], v[166:169], v[182:185], v[100:103]
	v_mfma_f32_16x16x32_bf16 v[92:95], v[146:149], v[214:217], v[92:95]
	v_mfma_f32_16x16x32_bf16 v[84:87], v[166:169], v[214:217], v[84:87]
	v_mfma_f32_16x16x32_bf16 v[76:79], v[146:149], v[222:225], v[76:79]
	v_mfma_f32_16x16x32_bf16 v[68:71], v[166:169], v[222:225], v[68:71]
	v_mfma_f32_16x16x32_bf16 v[124:127], v[150:153], v[178:181], v[124:127]
	v_mfma_f32_16x16x32_bf16 v[116:119], v[170:173], v[178:181], v[116:119]
	v_mfma_f32_16x16x32_bf16 v[108:111], v[150:153], v[186:189], v[108:111]
	v_mfma_f32_16x16x32_bf16 v[100:103], v[170:173], v[186:189], v[100:103]
	v_mfma_f32_16x16x32_bf16 v[92:95], v[150:153], v[218:221], v[92:95]
	v_mfma_f32_16x16x32_bf16 v[84:87], v[170:173], v[218:221], v[84:87]
	v_mfma_f32_16x16x32_bf16 v[76:79], v[150:153], v[226:229], v[76:79]
	v_mfma_f32_16x16x32_bf16 v[68:71], v[170:173], v[226:229], v[68:71]
	s_setprio 0
	s_barrier
	s_add_i32 s78, 0, 0x14000
	v_add_u32_e32 v138, s78, v142
	s_add_i32 s76, s76, s31
	ds_read_b128 v[230:233], v138
	ds_read_b128 v[234:237], v138 offset:1024
	ds_read_b128 v[238:241], v138 offset:2048
	ds_read_b128 v[242:245], v138 offset:3072
	v_lshl_add_u64 v[138:139], s[62:63], 0, v[158:159]
	s_mov_b32 m0, s76
	v_lshl_add_u64 v[154:155], s[62:63], 0, v[132:133]
	global_load_lds_dwordx4 v158, s[62:63]
	s_add_i32 m0, s76, 0x2000
	s_nop 0
	global_load_lds_dwordx4 v132, s[62:63]
	s_barrier
	s_waitcnt lgkmcnt(0)
	s_setprio 1
	s_waitcnt lgkmcnt(0)
	v_mfma_f32_16x16x32_bf16 v[120:123], v[230:233], v[174:177], v[120:123]
	v_mfma_f32_16x16x32_bf16 v[112:115], v[238:241], v[174:177], v[112:115]
	v_mfma_f32_16x16x32_bf16 v[104:107], v[230:233], v[182:185], v[104:107]
	v_mfma_f32_16x16x32_bf16 v[96:99], v[238:241], v[182:185], v[96:99]
	v_mfma_f32_16x16x32_bf16 v[88:91], v[230:233], v[214:217], v[88:91]
	v_mfma_f32_16x16x32_bf16 v[80:83], v[238:241], v[214:217], v[80:83]
	v_mfma_f32_16x16x32_bf16 v[72:75], v[230:233], v[222:225], v[72:75]
	v_mfma_f32_16x16x32_bf16 v[64:67], v[238:241], v[222:225], v[64:67]
	v_mfma_f32_16x16x32_bf16 v[120:123], v[234:237], v[178:181], v[120:123]
	v_mfma_f32_16x16x32_bf16 v[112:115], v[242:245], v[178:181], v[112:115]
	v_mfma_f32_16x16x32_bf16 v[104:107], v[234:237], v[186:189], v[104:107]
	v_mfma_f32_16x16x32_bf16 v[96:99], v[242:245], v[186:189], v[96:99]
	v_mfma_f32_16x16x32_bf16 v[88:91], v[234:237], v[218:221], v[88:91]
	v_mfma_f32_16x16x32_bf16 v[80:83], v[242:245], v[218:221], v[80:83]
	v_mfma_f32_16x16x32_bf16 v[72:75], v[234:237], v[226:229], v[72:75]
	v_mfma_f32_16x16x32_bf16 v[64:67], v[242:245], v[226:229], v[64:67]
	s_setprio 0
	s_mov_b32 m0, s48
	v_lshl_add_u64 v[190:191], s[66:67], 0, v[128:129]
	s_barrier
	ds_read_b128 v[174:177], v145 offset:16384
	ds_read_b128 v[178:181], v145 offset:17408
	ds_read_b128 v[182:185], v145 offset:18432
	ds_read_b128 v[186:189], v145 offset:19456
	ds_read_b128 v[214:217], v145 offset:20480
	ds_read_b128 v[218:221], v145 offset:21504
	ds_read_b128 v[222:225], v145 offset:22528
	ds_read_b128 v[226:229], v145 offset:23552
	global_load_lds_dwordx4 v128, s[66:67]
	v_lshl_add_u64 v[202:203], s[66:67], 0, v[130:131]
	s_mov_b32 m0, s50
	s_nop 0
	global_load_lds_dwordx4 v130, s[66:67]
	s_barrier
	s_waitcnt lgkmcnt(0)
	s_setprio 1
	s_waitcnt lgkmcnt(0)
	v_mfma_f32_16x16x32_bf16 v[60:63], v[146:149], v[174:177], v[60:63]
	v_mfma_f32_16x16x32_bf16 v[52:55], v[166:169], v[174:177], v[52:55]
	v_mfma_f32_16x16x32_bf16 v[44:47], v[146:149], v[182:185], v[44:47]
	v_mfma_f32_16x16x32_bf16 v[36:39], v[166:169], v[182:185], v[36:39]
	v_mfma_f32_16x16x32_bf16 v[28:31], v[146:149], v[214:217], v[28:31]
	v_mfma_f32_16x16x32_bf16 v[20:23], v[166:169], v[214:217], v[20:23]
	v_mfma_f32_16x16x32_bf16 v[12:15], v[146:149], v[222:225], v[12:15]
	v_mfma_f32_16x16x32_bf16 v[4:7], v[166:169], v[222:225], v[4:7]
	v_mfma_f32_16x16x32_bf16 v[60:63], v[150:153], v[178:181], v[60:63]
	v_mfma_f32_16x16x32_bf16 v[52:55], v[170:173], v[178:181], v[52:55]
	v_mfma_f32_16x16x32_bf16 v[44:47], v[150:153], v[186:189], v[44:47]
	v_mfma_f32_16x16x32_bf16 v[36:39], v[170:173], v[186:189], v[36:39]
	v_mfma_f32_16x16x32_bf16 v[28:31], v[150:153], v[218:221], v[28:31]
	v_mfma_f32_16x16x32_bf16 v[20:23], v[170:173], v[218:221], v[20:23]
	v_mfma_f32_16x16x32_bf16 v[12:15], v[150:153], v[226:229], v[12:15]
	v_mfma_f32_16x16x32_bf16 v[4:7], v[170:173], v[226:229], v[4:7]
	s_setprio 0
	s_barrier
	s_add_u32 s76, s62, 0x40000
	s_addc_u32 s77, s63, 0
	s_add_i32 s78, s78, s31
	s_mov_b32 m0, s78
	s_nop 0
	global_load_lds_dwordx4 v158, s[76:77]
	s_add_i32 m0, s78, 0x2000
	s_nop 0
	global_load_lds_dwordx4 v132, s[76:77]
	s_waitcnt vmcnt(6)
	s_barrier
	s_setprio 1
	v_mfma_f32_16x16x32_bf16 v[56:59], v[230:233], v[174:177], v[56:59]
	v_mfma_f32_16x16x32_bf16 v[48:51], v[238:241], v[174:177], v[48:51]
	v_mfma_f32_16x16x32_bf16 v[40:43], v[230:233], v[182:185], v[40:43]
	v_mfma_f32_16x16x32_bf16 v[32:35], v[238:241], v[182:185], v[32:35]
	v_mfma_f32_16x16x32_bf16 v[24:27], v[230:233], v[214:217], v[24:27]
	v_mfma_f32_16x16x32_bf16 v[16:19], v[238:241], v[214:217], v[16:19]
	v_mfma_f32_16x16x32_bf16 v[8:11], v[230:233], v[222:225], v[8:11]
	v_mfma_f32_16x16x32_bf16 v[0:3], v[238:241], v[222:225], v[0:3]
	v_mfma_f32_16x16x32_bf16 v[56:59], v[234:237], v[178:181], v[56:59]
	v_mfma_f32_16x16x32_bf16 v[48:51], v[242:245], v[178:181], v[48:51]
	v_mfma_f32_16x16x32_bf16 v[40:43], v[234:237], v[186:189], v[40:43]
	v_mfma_f32_16x16x32_bf16 v[32:35], v[242:245], v[186:189], v[32:35]
	v_mfma_f32_16x16x32_bf16 v[24:27], v[234:237], v[218:221], v[24:27]
	v_mfma_f32_16x16x32_bf16 v[16:19], v[242:245], v[218:221], v[16:19]
	v_mfma_f32_16x16x32_bf16 v[8:11], v[234:237], v[226:229], v[8:11]
	v_mfma_f32_16x16x32_bf16 v[0:3], v[242:245], v[226:229], v[0:3]
	s_setprio 0
	s_add_i32 s76, 0, 0x18000
	v_add_u32_e32 v140, s76, v142
	s_barrier
	ds_read_b128 v[146:149], v140
	ds_read_b128 v[150:153], v140 offset:1024
	ds_read_b128 v[166:169], v140 offset:2048
	ds_read_b128 v[170:173], v140 offset:3072
	s_add_u32 s66, s66, 0x40000
	s_addc_u32 s67, s67, 0
	s_mov_b32 m0, s65
	ds_read_b128 v[174:177], v145 offset:32768
	ds_read_b128 v[178:181], v145 offset:33792
	ds_read_b128 v[182:185], v145 offset:34816
	ds_read_b128 v[186:189], v145 offset:35840
	ds_read_b128 v[214:217], v145 offset:36864
	ds_read_b128 v[218:221], v145 offset:37888
	ds_read_b128 v[222:225], v145 offset:38912
	ds_read_b128 v[226:229], v145 offset:39936
	global_load_lds_dwordx4 v128, s[66:67]
	s_mov_b32 m0, s68
	s_nop 0
	global_load_lds_dwordx4 v130, s[66:67]
	s_waitcnt lgkmcnt(8)
	s_barrier
	s_waitcnt lgkmcnt(0)
	s_setprio 1
	s_waitcnt lgkmcnt(0)
	v_mfma_f32_16x16x32_bf16 v[124:127], v[146:149], v[174:177], v[124:127]
	v_mfma_f32_16x16x32_bf16 v[116:119], v[166:169], v[174:177], v[116:119]
	v_mfma_f32_16x16x32_bf16 v[108:111], v[146:149], v[182:185], v[108:111]
	v_mfma_f32_16x16x32_bf16 v[100:103], v[166:169], v[182:185], v[100:103]
	v_mfma_f32_16x16x32_bf16 v[92:95], v[146:149], v[214:217], v[92:95]
	v_mfma_f32_16x16x32_bf16 v[84:87], v[166:169], v[214:217], v[84:87]
	v_mfma_f32_16x16x32_bf16 v[76:79], v[146:149], v[222:225], v[76:79]
	v_mfma_f32_16x16x32_bf16 v[68:71], v[166:169], v[222:225], v[68:71]
	v_mfma_f32_16x16x32_bf16 v[124:127], v[150:153], v[178:181], v[124:127]
	v_mfma_f32_16x16x32_bf16 v[116:119], v[170:173], v[178:181], v[116:119]
	v_mfma_f32_16x16x32_bf16 v[108:111], v[150:153], v[186:189], v[108:111]
	v_mfma_f32_16x16x32_bf16 v[100:103], v[170:173], v[186:189], v[100:103]
	v_mfma_f32_16x16x32_bf16 v[92:95], v[150:153], v[218:221], v[92:95]
	v_mfma_f32_16x16x32_bf16 v[84:87], v[170:173], v[218:221], v[84:87]
	v_mfma_f32_16x16x32_bf16 v[76:79], v[150:153], v[226:229], v[76:79]
	v_mfma_f32_16x16x32_bf16 v[68:71], v[170:173], v[226:229], v[68:71]
	s_setprio 0
	s_barrier
	s_add_i32 s66, 0, 0x1c000
	s_add_i32 s67, s76, s31
	v_add_u32_e32 v140, s66, v142
	v_lshl_add_u64 v[138:139], v[138:139], 0, s[70:71]
	s_mov_b32 m0, s67
	ds_read_b128 v[230:233], v140
	ds_read_b128 v[234:237], v140 offset:1024
	ds_read_b128 v[238:241], v140 offset:2048
	ds_read_b128 v[242:245], v140 offset:3072
	global_load_lds_dwordx4 v[138:139], off
	v_lshl_add_u64 v[138:139], v[154:155], 0, s[70:71]
	s_add_i32 m0, s67, 0x2000
	s_nop 0
	global_load_lds_dwordx4 v[138:139], off
	s_barrier
	s_waitcnt lgkmcnt(0)
	s_setprio 1
	s_waitcnt lgkmcnt(0)
	v_mfma_f32_16x16x32_bf16 v[120:123], v[230:233], v[174:177], v[120:123]
	v_mfma_f32_16x16x32_bf16 v[112:115], v[238:241], v[174:177], v[112:115]
	v_mfma_f32_16x16x32_bf16 v[104:107], v[230:233], v[182:185], v[104:107]
	v_mfma_f32_16x16x32_bf16 v[96:99], v[238:241], v[182:185], v[96:99]
	v_mfma_f32_16x16x32_bf16 v[88:91], v[230:233], v[214:217], v[88:91]
	v_mfma_f32_16x16x32_bf16 v[80:83], v[238:241], v[214:217], v[80:83]
	v_mfma_f32_16x16x32_bf16 v[72:75], v[230:233], v[222:225], v[72:75]
	v_mfma_f32_16x16x32_bf16 v[64:67], v[238:241], v[222:225], v[64:67]
	v_mfma_f32_16x16x32_bf16 v[120:123], v[234:237], v[178:181], v[120:123]
	v_mfma_f32_16x16x32_bf16 v[112:115], v[242:245], v[178:181], v[112:115]
	v_mfma_f32_16x16x32_bf16 v[104:107], v[234:237], v[186:189], v[104:107]
	v_mfma_f32_16x16x32_bf16 v[96:99], v[242:245], v[186:189], v[96:99]
	v_mfma_f32_16x16x32_bf16 v[88:91], v[234:237], v[218:221], v[88:91]
	v_mfma_f32_16x16x32_bf16 v[80:83], v[242:245], v[218:221], v[80:83]
	v_mfma_f32_16x16x32_bf16 v[72:75], v[234:237], v[226:229], v[72:75]
	v_mfma_f32_16x16x32_bf16 v[64:67], v[242:245], v[226:229], v[64:67]
	s_setprio 0
	s_mov_b32 m0, s69
	v_lshl_add_u64 v[138:139], v[190:191], 0, s[70:71]
	s_barrier
	ds_read_b128 v[174:177], v145 offset:49152
	ds_read_b128 v[178:181], v145 offset:50176
	ds_read_b128 v[182:185], v145 offset:51200
	ds_read_b128 v[186:189], v145 offset:52224
	ds_read_b128 v[214:217], v145 offset:53248
	ds_read_b128 v[218:221], v145 offset:54272
	ds_read_b128 v[222:225], v145 offset:55296
	ds_read_b128 v[226:229], v145 offset:56320
	global_load_lds_dwordx4 v[138:139], off
	v_lshl_add_u64 v[138:139], v[202:203], 0, s[70:71]
	s_mov_b32 m0, s72
	s_nop 0
	global_load_lds_dwordx4 v[138:139], off
	s_barrier
	s_waitcnt lgkmcnt(0)
	s_setprio 1
	s_waitcnt lgkmcnt(0)
	v_mfma_f32_16x16x32_bf16 v[60:63], v[146:149], v[174:177], v[60:63]
	v_mfma_f32_16x16x32_bf16 v[52:55], v[166:169], v[174:177], v[52:55]
	v_mfma_f32_16x16x32_bf16 v[44:47], v[146:149], v[182:185], v[44:47]
	v_mfma_f32_16x16x32_bf16 v[36:39], v[166:169], v[182:185], v[36:39]
	v_mfma_f32_16x16x32_bf16 v[28:31], v[146:149], v[214:217], v[28:31]
	v_mfma_f32_16x16x32_bf16 v[20:23], v[166:169], v[214:217], v[20:23]
	v_mfma_f32_16x16x32_bf16 v[12:15], v[146:149], v[222:225], v[12:15]
	v_mfma_f32_16x16x32_bf16 v[4:7], v[166:169], v[222:225], v[4:7]
	v_mfma_f32_16x16x32_bf16 v[60:63], v[150:153], v[178:181], v[60:63]
	v_mfma_f32_16x16x32_bf16 v[52:55], v[170:173], v[178:181], v[52:55]
	v_mfma_f32_16x16x32_bf16 v[44:47], v[150:153], v[186:189], v[44:47]
	v_mfma_f32_16x16x32_bf16 v[36:39], v[170:173], v[186:189], v[36:39]
	v_mfma_f32_16x16x32_bf16 v[28:31], v[150:153], v[218:221], v[28:31]
	v_mfma_f32_16x16x32_bf16 v[20:23], v[170:173], v[218:221], v[20:23]
	v_mfma_f32_16x16x32_bf16 v[12:15], v[150:153], v[226:229], v[12:15]
	v_mfma_f32_16x16x32_bf16 v[4:7], v[170:173], v[226:229], v[4:7]
	s_setprio 0
	s_barrier
	s_add_u32 s62, s62, 0x40080
	s_addc_u32 s63, s63, 0
	s_add_i32 s66, s66, s31
	s_mov_b32 m0, s66
	s_nop 0
	global_load_lds_dwordx4 v158, s[62:63]
	s_add_i32 m0, s66, 0x2000
	s_nop 0
	global_load_lds_dwordx4 v132, s[62:63]
	s_waitcnt vmcnt(6)
	s_barrier
	s_setprio 1
	v_mfma_f32_16x16x32_bf16 v[56:59], v[230:233], v[174:177], v[56:59]
	v_mfma_f32_16x16x32_bf16 v[48:51], v[238:241], v[174:177], v[48:51]
	v_mfma_f32_16x16x32_bf16 v[40:43], v[230:233], v[182:185], v[40:43]
	v_mfma_f32_16x16x32_bf16 v[32:35], v[238:241], v[182:185], v[32:35]
	v_mfma_f32_16x16x32_bf16 v[24:27], v[230:233], v[214:217], v[24:27]
	v_mfma_f32_16x16x32_bf16 v[16:19], v[238:241], v[214:217], v[16:19]
	v_mfma_f32_16x16x32_bf16 v[8:11], v[230:233], v[222:225], v[8:11]
	v_mfma_f32_16x16x32_bf16 v[0:3], v[238:241], v[222:225], v[0:3]
	v_mfma_f32_16x16x32_bf16 v[56:59], v[234:237], v[178:181], v[56:59]
	v_mfma_f32_16x16x32_bf16 v[48:51], v[242:245], v[178:181], v[48:51]
	v_mfma_f32_16x16x32_bf16 v[40:43], v[234:237], v[186:189], v[40:43]
	v_mfma_f32_16x16x32_bf16 v[32:35], v[242:245], v[186:189], v[32:35]
	v_mfma_f32_16x16x32_bf16 v[24:27], v[234:237], v[218:221], v[24:27]
	v_mfma_f32_16x16x32_bf16 v[16:19], v[242:245], v[218:221], v[16:19]
	v_mfma_f32_16x16x32_bf16 v[8:11], v[234:237], v[226:229], v[8:11]
	v_mfma_f32_16x16x32_bf16 v[0:3], v[242:245], v[226:229], v[0:3]
	s_setprio 0
	s_add_i32 s75, s75, 2
	s_add_u32 s58, s58, 0x100
	s_addc_u32 s59, s59, 0
	s_add_u32 s43, s43, 0x100
	s_addc_u32 s51, s51, 0
	s_add_u32 s62, s58, 0xfffc0080
	s_addc_u32 s63, s59, -1
	s_add_i32 s76, 0, 0x10000
	v_add_u32_e32 v138, s76, v142
	s_cmp_gt_u32 s75, 13
	s_barrier
	s_cbranch_scc0 .LBB0_792
